# GEMM mainloops: same as previous but the static s_setprio 1 goes to waves 0-3 instead of 4-7 (per-half comparison)
# baseline (speedup 1.0000x reference)
; #define PG8_LDA(dst, b, h) do { _Pragma("unroll") for (int m = 0; m < 4; ++m) _Pragma("unroll") for (int k = 0; k < 2; ++k) dst[m][k] = *(const LAS bf16x8*)(lds + PG8_SA(b, h) + aoff + m * 2048 + k * 1024); } while (0)
; template <class Epi>
; DI void gemm_phase(ldsp lds, const Gemm g, const StaticOrder S, const Epi E) {
;     ...
;         const bool has_next = S.next(ui + 1, nxt);
;         const char* nA = has_next ? (const char*)g.A + (size_t)nxt.pm * tstepA : cA; const char* nB = has_next ? (const char*)g.Bt + (size_t)nxt.pn * tstepB : cB;
;         for (int t = 0; t < nt; t += 2) {
;             const bool last = (t == nt - 2);
;             const char* a1 = cA + (size_t)(t + 1) * kstep;
;             const char* a2 = last ? nA : cA + (size_t)(t + 2) * kstep; const char* b2 = last ? nB : cB + (size_t)(t + 2) * kstep;
;             const char* a3 = a2 + kstep; const char* b3 = b2 + kstep;
;             PG8_LDB(B0, 0, 0); PG8_LDB(B1, 0, 1); PG8_SCHED; PG8_LDA(At, 0, 0); PG8_STAGE(PG8_SA(1, 1), a1 + hstepA, voffA);
;             PG8_WAIT_V(8); PG8_WAIT_L(0); PG8_BAR; PG8_MMA(0, 0, At, B0); PG8_MMA(0, 1, At, B1); PG8_BAR; PG8_SCHED;
;             PG8_LDA(At, 0, 1); PG8_STAGE(PG8_SB(0, 0), b2, voffB); PG8_STAGE(PG8_SB(0, 1), b2 + hstepB, voffB); PG8_STAGE(PG8_SA(0, 0), a2, voffA);
;             PG8_WAIT_V(8); PG8_WAIT_L(0); PG8_BAR; PG8_MMA(1, 0, At, B0); PG8_MMA(1, 1, At, B1); PG8_BAR; PG8_SCHED;
;             PG8_LDB(B0, 1, 0); PG8_LDB(B1, 1, 1); PG8_SCHED; PG8_LDA(At, 1, 0); PG8_STAGE(PG8_SA(0, 1), a2 + hstepA, voffA);
;             PG8_WAIT_V(8); PG8_WAIT_L(0); PG8_BAR; PG8_MMA(0, 0, At, B0); PG8_MMA(0, 1, At, B1); PG8_BAR; PG8_SCHED;
;             PG8_LDA(At, 1, 1); PG8_STAGE(PG8_SB(1, 0), b3, voffB); PG8_STAGE(PG8_SB(1, 1), b3 + hstepB, voffB); PG8_STAGE(PG8_SA(1, 0), a3, voffA);
;             PG8_WAIT_V(8); PG8_WAIT_L(0); PG8_BAR; PG8_MMA(1, 0, At, B0); PG8_MMA(1, 1, At, B1); PG8_BAR; PG8_SCHED;
;         }
;         if (wr == 0) PG8_BAR;
;         E(acc, cur, wr, wc, fr, fq);
;         if (!has_next) break;
; #pragma unroll
;         for (int a = 0; a < 2; ++a)
; #pragma unroll
;             for (int b = 0; b < 2; ++b)
; #pragma unroll
;                 for (int m = 0; m < 4; ++m)
; #pragma unroll
;                     for (int n = 0; n < 2; ++n) acc[a][b][m][n] = (f32x4){0.f, 0.f, 0.f, 0.f};
;         cur = nxt; cA = nA; cB = nB; ++ui;
.LBB0_186:
	s_ashr_i32 s11, s10, 31
	s_lshl_b64 s[12:13], s[10:11], 19
	s_add_u32 s12, s25, s12
	s_addc_u32 s13, s26, s13
	s_and_b64 s[14:15], s[0:1], exec
	s_cselect_b32 s11, s13, s19
	s_cselect_b32 s40, s12, s18
	s_ashr_i32 s9, s8, 31
	s_lshl_b64 s[14:15], s[8:9], 19
	s_add_u32 s14, s27, s14
	s_addc_u32 s15, s29, s15
	s_and_b64 s[22:23], s[0:1], exec
	s_cselect_b32 s9, s15, s21
	s_cselect_b32 s41, s14, s20
	s_add_u32 s18, s18, 0x40080
	s_addc_u32 s19, s19, 0
	s_add_u32 s42, s20, 0x100
	v_mov_b32_e32 v2, 0
	s_addc_u32 s43, s21, 0
	s_mov_b32 s44, -2
	v_mov_b32_e32 v3, v2
	v_mov_b32_e32 v4, v2
	v_mov_b32_e32 v5, v2
	v_mov_b32_e32 v6, v2
	v_mov_b32_e32 v7, v2
	v_mov_b32_e32 v8, v2
	v_mov_b32_e32 v9, v2
	v_mov_b32_e32 v18, v2
	v_mov_b32_e32 v19, v2
	v_mov_b32_e32 v20, v2
	v_mov_b32_e32 v21, v2
	v_mov_b32_e32 v22, v2
	v_mov_b32_e32 v23, v2
	v_mov_b32_e32 v24, v2
	v_mov_b32_e32 v25, v2
	v_mov_b32_e32 v34, v2
	v_mov_b32_e32 v35, v2
	v_mov_b32_e32 v36, v2
	v_mov_b32_e32 v37, v2
	v_mov_b32_e32 v38, v2
	v_mov_b32_e32 v39, v2
	v_mov_b32_e32 v40, v2
	v_mov_b32_e32 v41, v2
	v_mov_b32_e32 v50, v2
	v_mov_b32_e32 v51, v2
	v_mov_b32_e32 v52, v2
	v_mov_b32_e32 v53, v2
	v_mov_b32_e32 v54, v2
	v_mov_b32_e32 v55, v2
	v_mov_b32_e32 v56, v2
	v_mov_b32_e32 v57, v2
	v_mov_b32_e32 v10, v2
	v_mov_b32_e32 v11, v2
	v_mov_b32_e32 v12, v2
	v_mov_b32_e32 v13, v2
	v_mov_b32_e32 v14, v2
	v_mov_b32_e32 v15, v2
	v_mov_b32_e32 v16, v2
	v_mov_b32_e32 v17, v2
	v_mov_b32_e32 v26, v2
	v_mov_b32_e32 v27, v2
	v_mov_b32_e32 v28, v2
	v_mov_b32_e32 v29, v2
	v_mov_b32_e32 v30, v2
	v_mov_b32_e32 v31, v2
	v_mov_b32_e32 v32, v2
	v_mov_b32_e32 v33, v2
	v_mov_b32_e32 v42, v2
	v_mov_b32_e32 v43, v2
	v_mov_b32_e32 v44, v2
	v_mov_b32_e32 v45, v2
	v_mov_b32_e32 v46, v2
	v_mov_b32_e32 v47, v2
	v_mov_b32_e32 v48, v2
	v_mov_b32_e32 v49, v2
	v_mov_b32_e32 v58, v2
	v_mov_b32_e32 v59, v2
	v_mov_b32_e32 v60, v2
	v_mov_b32_e32 v61, v2
	v_mov_b32_e32 v62, v2
	v_mov_b32_e32 v63, v2
	v_mov_b32_e32 v64, v2
	v_mov_b32_e32 v65, v2
	v_mov_b32_e32 v66, v2
	v_mov_b32_e32 v67, v2
	v_mov_b32_e32 v68, v2
	v_mov_b32_e32 v69, v2
	v_mov_b32_e32 v70, v2
	v_mov_b32_e32 v71, v2
	v_mov_b32_e32 v72, v2
	v_mov_b32_e32 v73, v2
	v_mov_b32_e32 v82, v2
	v_mov_b32_e32 v83, v2
	v_mov_b32_e32 v84, v2
	v_mov_b32_e32 v85, v2
	v_mov_b32_e32 v86, v2
	v_mov_b32_e32 v87, v2
	v_mov_b32_e32 v88, v2
	v_mov_b32_e32 v89, v2
	v_mov_b32_e32 v98, v2
	v_mov_b32_e32 v99, v2
	v_mov_b32_e32 v100, v2
	v_mov_b32_e32 v101, v2
	v_mov_b32_e32 v102, v2
	v_mov_b32_e32 v103, v2
	v_mov_b32_e32 v104, v2
	v_mov_b32_e32 v105, v2
	v_mov_b32_e32 v114, v2
	v_mov_b32_e32 v115, v2
	v_mov_b32_e32 v116, v2
	v_mov_b32_e32 v117, v2
	v_mov_b32_e32 v118, v2
	v_mov_b32_e32 v119, v2
	v_mov_b32_e32 v120, v2
	v_mov_b32_e32 v121, v2
	v_mov_b32_e32 v74, v2
	v_mov_b32_e32 v75, v2
	v_mov_b32_e32 v76, v2
	v_mov_b32_e32 v77, v2
	v_mov_b32_e32 v78, v2
	v_mov_b32_e32 v79, v2
	v_mov_b32_e32 v80, v2
	v_mov_b32_e32 v81, v2
	v_mov_b32_e32 v90, v2
	v_mov_b32_e32 v91, v2
	v_mov_b32_e32 v92, v2
	v_mov_b32_e32 v93, v2
	v_mov_b32_e32 v94, v2
	v_mov_b32_e32 v95, v2
	v_mov_b32_e32 v96, v2
	v_mov_b32_e32 v97, v2
	v_mov_b32_e32 v106, v2
	v_mov_b32_e32 v107, v2
	v_mov_b32_e32 v108, v2
	v_mov_b32_e32 v109, v2
	v_mov_b32_e32 v110, v2
	v_mov_b32_e32 v111, v2
	v_mov_b32_e32 v112, v2
	v_mov_b32_e32 v113, v2
	v_mov_b32_e32 v122, v2
	v_mov_b32_e32 v123, v2
	v_mov_b32_e32 v124, v2
	v_mov_b32_e32 v125, v2
	v_mov_b32_e32 v126, v2
	v_mov_b32_e32 v127, v2
	v_mov_b32_e32 v128, v2
	v_mov_b32_e32 v129, v2
	v_readfirstlane_b32 s32, v153
	s_nop 3
	s_lshr_b32 s32, s32, 6
	s_cmp_ge_u32 s32, 4
	s_cbranch_scc1 .Lgemm_prio_skip1
	s_setprio 1

; #define PG8_BAR __builtin_amdgcn_s_barrier()
; template <class Epi>
; DI void gemm_phase(ldsp lds, const Gemm g, const StaticOrder S, const Epi E) {
;     ...
; #pragma unroll
;         for (int a = 0; a < 2; ++a)
; #pragma unroll
;             for (int b = 0; b < 2; ++b)
; #pragma unroll
;                 for (int m = 0; m < 4; ++m)
; #pragma unroll
;                     for (int n = 0; n < 2; ++n) acc[a][b][m][n] = (f32x4){0.f, 0.f, 0.f, 0.f};
;         cur = nxt; cA = nA; cB = nB; ++ui;
;         if (wr == 1) PG8_BAR;
.LBB0_414:
	s_add_u32 s4, s28, 0x80
	s_addc_u32 s5, s29, 0
	s_add_u32 s28, s26, 0x100
	v_mov_b32_e32 v2, 0
	s_addc_u32 s29, s27, 0
	s_mov_b32 s26, 0
	v_mov_b32_e32 v3, v2
	v_mov_b32_e32 v4, v2
	v_mov_b32_e32 v5, v2
	v_mov_b32_e32 v6, v2
	v_mov_b32_e32 v7, v2
	v_mov_b32_e32 v8, v2
	v_mov_b32_e32 v9, v2
	v_mov_b32_e32 v14, v2
	v_mov_b32_e32 v15, v2
	v_mov_b32_e32 v16, v2
	v_mov_b32_e32 v17, v2
	v_mov_b32_e32 v22, v2
	v_mov_b32_e32 v23, v2
	v_mov_b32_e32 v24, v2
	v_mov_b32_e32 v25, v2
	v_mov_b32_e32 v30, v2
	v_mov_b32_e32 v31, v2
	v_mov_b32_e32 v32, v2
	v_mov_b32_e32 v33, v2
	v_mov_b32_e32 v38, v2
	v_mov_b32_e32 v39, v2
	v_mov_b32_e32 v40, v2
	v_mov_b32_e32 v41, v2
	v_mov_b32_e32 v46, v2
	v_mov_b32_e32 v47, v2
	v_mov_b32_e32 v48, v2
	v_mov_b32_e32 v49, v2
	v_mov_b32_e32 v54, v2
	v_mov_b32_e32 v55, v2
	v_mov_b32_e32 v56, v2
	v_mov_b32_e32 v57, v2
	v_mov_b32_e32 v10, v2
	v_mov_b32_e32 v11, v2
	v_mov_b32_e32 v12, v2
	v_mov_b32_e32 v13, v2
	v_mov_b32_e32 v18, v2
	v_mov_b32_e32 v19, v2
	v_mov_b32_e32 v20, v2
	v_mov_b32_e32 v21, v2
	v_mov_b32_e32 v26, v2
	v_mov_b32_e32 v27, v2
	v_mov_b32_e32 v28, v2
	v_mov_b32_e32 v29, v2
	v_mov_b32_e32 v34, v2
	v_mov_b32_e32 v35, v2
	v_mov_b32_e32 v36, v2
	v_mov_b32_e32 v37, v2
	v_mov_b32_e32 v42, v2
	v_mov_b32_e32 v43, v2
	v_mov_b32_e32 v44, v2
	v_mov_b32_e32 v45, v2
	v_mov_b32_e32 v50, v2
	v_mov_b32_e32 v51, v2
	v_mov_b32_e32 v52, v2
	v_mov_b32_e32 v53, v2
	v_mov_b32_e32 v58, v2
	v_mov_b32_e32 v59, v2
	v_mov_b32_e32 v60, v2
	v_mov_b32_e32 v61, v2
	v_mov_b32_e32 v62, v2
	v_mov_b32_e32 v63, v2
	v_mov_b32_e32 v64, v2
	v_mov_b32_e32 v65, v2
	v_mov_b32_e32 v66, v2
	v_mov_b32_e32 v67, v2
	v_mov_b32_e32 v68, v2
	v_mov_b32_e32 v69, v2
	v_mov_b32_e32 v70, v2
	v_mov_b32_e32 v71, v2
	v_mov_b32_e32 v72, v2
	v_mov_b32_e32 v73, v2
	v_mov_b32_e32 v78, v2
	v_mov_b32_e32 v79, v2
	v_mov_b32_e32 v80, v2
	v_mov_b32_e32 v81, v2
	v_mov_b32_e32 v86, v2
	v_mov_b32_e32 v87, v2
	v_mov_b32_e32 v88, v2
	v_mov_b32_e32 v89, v2
	v_mov_b32_e32 v94, v2
	v_mov_b32_e32 v95, v2
	v_mov_b32_e32 v96, v2
	v_mov_b32_e32 v97, v2
	v_mov_b32_e32 v102, v2
	v_mov_b32_e32 v103, v2
	v_mov_b32_e32 v104, v2
	v_mov_b32_e32 v105, v2
	v_mov_b32_e32 v110, v2
	v_mov_b32_e32 v111, v2
	v_mov_b32_e32 v112, v2
	v_mov_b32_e32 v113, v2
	v_mov_b32_e32 v118, v2
	v_mov_b32_e32 v119, v2
	v_mov_b32_e32 v120, v2
	v_mov_b32_e32 v121, v2
	v_mov_b32_e32 v74, v2
	v_mov_b32_e32 v75, v2
	v_mov_b32_e32 v76, v2
	v_mov_b32_e32 v77, v2
	v_mov_b32_e32 v82, v2
	v_mov_b32_e32 v83, v2
	v_mov_b32_e32 v84, v2
	v_mov_b32_e32 v85, v2
	v_mov_b32_e32 v90, v2
	v_mov_b32_e32 v91, v2
	v_mov_b32_e32 v92, v2
	v_mov_b32_e32 v93, v2
	v_mov_b32_e32 v98, v2
	v_mov_b32_e32 v99, v2
	v_mov_b32_e32 v100, v2
	v_mov_b32_e32 v101, v2
	v_mov_b32_e32 v106, v2
	v_mov_b32_e32 v107, v2
	v_mov_b32_e32 v108, v2
	v_mov_b32_e32 v109, v2
	v_mov_b32_e32 v114, v2
	v_mov_b32_e32 v115, v2
	v_mov_b32_e32 v116, v2
	v_mov_b32_e32 v117, v2
	v_mov_b32_e32 v122, v2
	v_mov_b32_e32 v123, v2
	v_mov_b32_e32 v124, v2
	v_mov_b32_e32 v125, v2
	v_mov_b32_e32 v126, v2
	v_mov_b32_e32 v127, v2
	v_mov_b32_e32 v128, v2
	v_mov_b32_e32 v129, v2
	v_readfirstlane_b32 s32, v153
	s_nop 3
	s_lshr_b32 s32, s32, 6
	s_cmp_ge_u32 s32, 4
	s_cbranch_scc1 .Lgemm_prio_skip2
	s_setprio 1

; #define PG8_BAR __builtin_amdgcn_s_barrier()
; template <class Epi>
; DI void gemm_phase(ldsp lds, const Gemm g, const StaticOrder S, const Epi E) {
;     ...
; #pragma unroll
;         for (int a = 0; a < 2; ++a)
; #pragma unroll
;             for (int b = 0; b < 2; ++b)
; #pragma unroll
;                 for (int m = 0; m < 4; ++m)
; #pragma unroll
;                     for (int n = 0; n < 2; ++n) acc[a][b][m][n] = (f32x4){0.f, 0.f, 0.f, 0.f};
;         cur = nxt; cA = nA; cB = nB; ++ui;
;         if (wr == 1) PG8_BAR;
.LBB0_944:
	s_add_u32 s20, s20, 0x80
	s_addc_u32 s21, s21, 0
	s_add_u32 s44, s22, 0x100
	v_mov_b32_e32 v2, 0
	s_addc_u32 s45, s23, 0
	s_mov_b32 s22, 0
	v_mov_b32_e32 v3, v2
	v_mov_b32_e32 v4, v2
	v_mov_b32_e32 v5, v2
	v_mov_b32_e32 v6, v2
	v_mov_b32_e32 v7, v2
	v_mov_b32_e32 v8, v2
	v_mov_b32_e32 v9, v2
	v_mov_b32_e32 v10, v2
	v_mov_b32_e32 v11, v2
	v_mov_b32_e32 v12, v2
	v_mov_b32_e32 v13, v2
	v_mov_b32_e32 v22, v2
	v_mov_b32_e32 v23, v2
	v_mov_b32_e32 v24, v2
	v_mov_b32_e32 v25, v2
	v_mov_b32_e32 v26, v2
	v_mov_b32_e32 v27, v2
	v_mov_b32_e32 v28, v2
	v_mov_b32_e32 v29, v2
	v_mov_b32_e32 v38, v2
	v_mov_b32_e32 v39, v2
	v_mov_b32_e32 v40, v2
	v_mov_b32_e32 v41, v2
	v_mov_b32_e32 v42, v2
	v_mov_b32_e32 v43, v2
	v_mov_b32_e32 v44, v2
	v_mov_b32_e32 v45, v2
	v_mov_b32_e32 v54, v2
	v_mov_b32_e32 v55, v2
	v_mov_b32_e32 v56, v2
	v_mov_b32_e32 v57, v2
	v_mov_b32_e32 v14, v2
	v_mov_b32_e32 v15, v2
	v_mov_b32_e32 v16, v2
	v_mov_b32_e32 v17, v2
	v_mov_b32_e32 v18, v2
	v_mov_b32_e32 v19, v2
	v_mov_b32_e32 v20, v2
	v_mov_b32_e32 v21, v2
	v_mov_b32_e32 v30, v2
	v_mov_b32_e32 v31, v2
	v_mov_b32_e32 v32, v2
	v_mov_b32_e32 v33, v2
	v_mov_b32_e32 v34, v2
	v_mov_b32_e32 v35, v2
	v_mov_b32_e32 v36, v2
	v_mov_b32_e32 v37, v2
	v_mov_b32_e32 v46, v2
	v_mov_b32_e32 v47, v2
	v_mov_b32_e32 v48, v2
	v_mov_b32_e32 v49, v2
	v_mov_b32_e32 v50, v2
	v_mov_b32_e32 v51, v2
	v_mov_b32_e32 v52, v2
	v_mov_b32_e32 v53, v2
	v_mov_b32_e32 v58, v2
	v_mov_b32_e32 v59, v2
	v_mov_b32_e32 v60, v2
	v_mov_b32_e32 v61, v2
	v_mov_b32_e32 v62, v2
	v_mov_b32_e32 v63, v2
	v_mov_b32_e32 v64, v2
	v_mov_b32_e32 v65, v2
	v_mov_b32_e32 v66, v2
	v_mov_b32_e32 v67, v2
	v_mov_b32_e32 v68, v2
	v_mov_b32_e32 v69, v2
	v_mov_b32_e32 v70, v2
	v_mov_b32_e32 v71, v2
	v_mov_b32_e32 v72, v2
	v_mov_b32_e32 v73, v2
	v_mov_b32_e32 v74, v2
	v_mov_b32_e32 v75, v2
	v_mov_b32_e32 v76, v2
	v_mov_b32_e32 v77, v2
	v_mov_b32_e32 v86, v2
	v_mov_b32_e32 v87, v2
	v_mov_b32_e32 v88, v2
	v_mov_b32_e32 v89, v2
	v_mov_b32_e32 v90, v2
	v_mov_b32_e32 v91, v2
	v_mov_b32_e32 v92, v2
	v_mov_b32_e32 v93, v2
	v_mov_b32_e32 v102, v2
	v_mov_b32_e32 v103, v2
	v_mov_b32_e32 v104, v2
	v_mov_b32_e32 v105, v2
	v_mov_b32_e32 v106, v2
	v_mov_b32_e32 v107, v2
	v_mov_b32_e32 v108, v2
	v_mov_b32_e32 v109, v2
	v_mov_b32_e32 v118, v2
	v_mov_b32_e32 v119, v2
	v_mov_b32_e32 v120, v2
	v_mov_b32_e32 v121, v2
	v_mov_b32_e32 v78, v2
	v_mov_b32_e32 v79, v2
	v_mov_b32_e32 v80, v2
	v_mov_b32_e32 v81, v2
	v_mov_b32_e32 v82, v2
	v_mov_b32_e32 v83, v2
	v_mov_b32_e32 v84, v2
	v_mov_b32_e32 v85, v2
	v_mov_b32_e32 v94, v2
	v_mov_b32_e32 v95, v2
	v_mov_b32_e32 v96, v2
	v_mov_b32_e32 v97, v2
	v_mov_b32_e32 v98, v2
	v_mov_b32_e32 v99, v2
	v_mov_b32_e32 v100, v2
	v_mov_b32_e32 v101, v2
	v_mov_b32_e32 v110, v2
	v_mov_b32_e32 v111, v2
	v_mov_b32_e32 v112, v2
	v_mov_b32_e32 v113, v2
	v_mov_b32_e32 v114, v2
	v_mov_b32_e32 v115, v2
	v_mov_b32_e32 v116, v2
	v_mov_b32_e32 v117, v2
	v_mov_b32_e32 v122, v2
	v_mov_b32_e32 v123, v2
	v_mov_b32_e32 v124, v2
	v_mov_b32_e32 v125, v2
	v_mov_b32_e32 v126, v2
	v_mov_b32_e32 v127, v2
	v_mov_b32_e32 v128, v2
	v_mov_b32_e32 v129, v2
	v_readfirstlane_b32 s32, v153
	s_nop 3
	s_lshr_b32 s32, s32, 6
	s_cmp_ge_u32 s32, 4
	s_cbranch_scc1 .Lgemm_prio_skip3
	s_setprio 1
